# skip the unused start-of-kernel cooperative_groups grid.sync (all workgroups skip it uniformly; XCD barrier census unchanged)
# speedup vs baseline: 1.0126x; 1.0008x over previous
; #define LAS __attribute__((address_space(3)))
; __global__ void __launch_bounds__(512, 2) mega(Params P) {
;     extern __shared__ __attribute__((aligned(16))) unsigned char lds_raw[];
;     LAS unsigned char* lds = (LAS unsigned char*)lds_raw;
;     cg::grid_group grid = cg::this_grid();
;     const int tid = threadIdx.x, lane = tid & 63, wave = __builtin_amdgcn_readfirstlane(tid >> 6);
;     const int G = gridDim.x, cb = blockIdx.x, gw = cb * 8 + wave, NGW = G * 8;
;     volatile LAS unsigned* xst = (volatile LAS unsigned*)(lds + 131072);
;     if (tid < 16) xst[tid] = 0u;
;     __syncthreads();
;     grid.sync();
;     (void)xcd_barrier_post((unsigned*)(P.ws + WS_BAR), xst);
_Z4mega6Params:
	s_load_dword s36, s[0:1], 0x88
	s_load_dwordx2 s[68:69], s[0:1], 0x80
	s_add_u32 s4, s0, 0x80
	v_and_b32_e32 v238, 0x3ff, v0
	s_mov_b32 s33, s2
	s_addc_u32 s5, s1, 0
	s_movk_i32 s6, 0x3ff
	v_readfirstlane_b32 s20, v238
	v_cmp_gt_u32_e32 vcc, 16, v238
	s_and_saveexec_b64 s[2:3], vcc
	v_lshl_add_u32 v1, v238, 2, 0
	v_add_u32_e32 v1, 0x20000, v1
	v_mov_b32_e32 v2, 0
	ds_write_b32 v1, v2
	s_or_b64 exec, exec, s[2:3]
	v_lshrrev_b32_e32 v1, 20, v0
	v_lshrrev_b32_e32 v0, 10, v0
	v_or_b32_e32 v0, v0, v1
	v_and_or_b32 v0, v0, s6, v238
	v_cmp_eq_u32_e32 vcc, 0, v0
	s_waitcnt lgkmcnt(0)
	s_barrier
	s_barrier
	s_and_saveexec_b64 s[2:3], vcc
	s_branch .LBB0_12
	buffer_wbl2 sc1
	s_load_dwordx2 s[4:5], s[4:5], 0x58
	s_mov_b64 s[6:7], exec
	v_mbcnt_lo_u32_b32 v0, s6, 0
	v_mbcnt_hi_u32_b32 v0, s7, v0
	v_cmp_eq_u32_e32 vcc, 0, v0
	s_waitcnt lgkmcnt(0)
	s_load_dword s10, s[4:5], 0x28
	s_and_saveexec_b64 s[8:9], vcc
	s_cbranch_execz .LBB0_5
	s_bcnt1_i32_b64 s6, s[6:7]
	v_mov_b32_e32 v1, 0
	v_mov_b32_e32 v2, s6
	global_atomic_add v1, v1, v2, s[4:5] offset:32 sc0
